# retention main unit de-serialised: 16 V fragment LDS reads issued at the top of each jt iteration, the 8 gate-row loads of the epilogue issued together
# baseline (speedup 1.0000x reference)
; #define LAS __attribute__((address_space(3)))
; #define MFMA32(a, b, c) __builtin_amdgcn_mfma_f32_32x32x16_bf16((a), (b), (c), 0, 0, 0)
; __device__ __forceinline__ int crow(int reg, int h) { return (reg & 3) + 8 * (reg >> 2) + 4 * h; }
; __device__ __forceinline__ s16x4 tr_read(const LAS unsigned char* p) { return __builtin_bit_cast(s16x4, __builtin_amdgcn_ds_read_tr16_b64_v4i16((LAS s16x4*)p)); }
; __device__ __forceinline__ bf16x8 cat8(s16x4 lo, s16x4 hi) { return __builtin_shufflevector(lo, hi, 0, 1, 2, 3, 4, 5, 6, 7); }
; __device__ __forceinline__ void main_unit(LAS unsigned char* lds, const bf16_t* __restrict__ proj, const bf16_t* __restrict__ sprevT, bf16_t* __restrict__ y,
;                                           const float* __restrict__ rnorm, int b, int h, int n) {
;     ...
;     for (int jt = 0; jt <= ig; ++jt) {
;         f32x16 st = zero16();
;         const bf16_t* kp = proj + (row0 + jt * 32 + r) * DIN + C_RK + h * 128 + hh * 8;
;         bf16x8 ka[8];
; #pragma unroll
;         for (int s = 0; s < 8; ++s) ka[s] = *(const bf16x8*)(kp + s * 16);
; #pragma unroll
;         for (int s = 0; s < 8; ++s) st = MFMA32(ka[s], qf[s], st);
; #pragma unroll
;         for (int i = 0; i < 16; ++i) {
;             const int d = iloc - (jt * 32 + crow(i, hh));
;             const float f = __builtin_amdgcn_exp2f(l2g * (float)d) * 0.08838834764831845f;
;             st[i] = d >= 0 ? st[i] * f : 0.f;
;         }
; #pragma unroll
;         for (int s2 = 0; s2 < 2; ++s2) {
;             const bf16x8 pb = pack_step(st, s2);
;             const LAS unsigned char* vp = va + (jt * 32 + 16 * s2) * VSTR;
; #pragma unroll
;             for (int t = 0; t < 4; ++t) { const bf16x8 a = cat8(tr_read(vp + t * 64), tr_read(vp + 8 * VSTR + t * 64)); acc[t] = MFMA32(a, pb, acc[t]); }
.LBB0_392:
	v_add_u32_e32 v250, s2, v153
	ds_read_b64_tr_b16 v[218:219], v250
	ds_read_b64_tr_b16 v[220:221], v250 offset:4608
	ds_read_b64_tr_b16 v[222:223], v250 offset:64
	ds_read_b64_tr_b16 v[224:225], v250 offset:4672
	ds_read_b64_tr_b16 v[226:227], v250 offset:128
	ds_read_b64_tr_b16 v[228:229], v250 offset:4736
	ds_read_b64_tr_b16 v[230:231], v250 offset:192
	ds_read_b64_tr_b16 v[232:233], v250 offset:4800
	ds_read_b64_tr_b16 v[234:235], v250 offset:9216
	ds_read_b64_tr_b16 v[236:237], v250 offset:13824
	ds_read_b64_tr_b16 v[238:239], v250 offset:9280
	ds_read_b64_tr_b16 v[240:241], v250 offset:13888
	ds_read_b64_tr_b16 v[242:243], v250 offset:9344
	ds_read_b64_tr_b16 v[244:245], v250 offset:13952
	ds_read_b64_tr_b16 v[246:247], v250 offset:9408
	ds_read_b64_tr_b16 v[248:249], v250 offset:14016
	v_add_u32_e32 v68, s16, v149
	v_mov_b64_e32 v[66:67], s[6:7]
	v_mad_u64_u32 v[66:67], s[10:11], v68, s35, v[66:67]
	v_lshl_add_u64 v[66:67], v[66:67], 0, s[8:9]
	v_lshl_add_u64 v[66:67], v[66:67], 0, v[0:1]
	s_mov_b64 s[10:11], 0x1c00
	v_lshl_add_u64 v[70:71], v[66:67], 0, s[10:11]
	v_add_co_u32_e32 v66, vcc, 0x1000, v66
	v_add_u32_e32 v155, v149, v154
	s_nop 0
	v_addc_co_u32_e32 v67, vcc, 0, v67, vcc
	global_load_dwordx4 v[66:69], v[66:67], off offset:3072
	s_nop 0
	global_load_dwordx4 v[156:159], v[70:71], off offset:32
	global_load_dwordx4 v[162:165], v[70:71], off offset:64
	global_load_dwordx4 v[166:169], v[70:71], off offset:96
	global_load_dwordx4 v[170:173], v[70:71], off offset:128
	global_load_dwordx4 v[174:177], v[70:71], off offset:160
	global_load_dwordx4 v[178:181], v[70:71], off offset:192
	global_load_dwordx4 v[186:189], v[70:71], off offset:224
	v_cmp_lt_i32_e32 vcc, -1, v155
	s_add_i32 s16, s16, 32
	v_subrev_u32_e32 v154, 32, v154
	s_waitcnt vmcnt(7)
	v_mfma_f32_32x32x16_bf16 v[66:81], v[66:69], v[82:85], 0
	s_waitcnt vmcnt(6)
	v_mfma_f32_32x32x16_bf16 v[66:81], v[156:159], v[86:89], v[66:81]
	v_cvt_f32_i32_e32 v156, v155
	v_mul_f32_e32 v156, v151, v156
	v_exp_f32_e32 v156, v156
	s_waitcnt vmcnt(5)
	v_mfma_f32_32x32x16_bf16 v[66:81], v[162:165], v[94:97], v[66:81]
	v_mul_f32_e32 v156, 0x3db504f3, v156
	s_waitcnt vmcnt(4)
	v_mfma_f32_32x32x16_bf16 v[66:81], v[166:169], v[98:101], v[66:81]
	s_waitcnt vmcnt(3)
	v_mfma_f32_32x32x16_bf16 v[66:81], v[170:173], v[102:105], v[66:81]
	s_waitcnt vmcnt(2)
	v_mfma_f32_32x32x16_bf16 v[66:81], v[174:177], v[106:109], v[66:81]
	s_waitcnt vmcnt(1)
	v_mfma_f32_32x32x16_bf16 v[66:81], v[178:181], v[110:113], v[66:81]
	s_waitcnt vmcnt(0)
	v_mfma_f32_32x32x16_bf16 v[66:81], v[186:189], v[90:93], v[66:81]
	s_nop 11
	v_mul_f32_e32 v66, v156, v66
	v_add_u32_e32 v156, -1, v155
	v_cndmask_b32_e32 v66, 0, v66, vcc
	v_cmp_lt_i32_e32 vcc, -1, v156
	v_cvt_f32_i32_e32 v156, v156
	v_mul_f32_e32 v156, v151, v156
	v_exp_f32_e32 v156, v156
	s_nop 0
	v_mul_f32_e32 v156, 0x3db504f3, v156
	v_mul_f32_e32 v67, v156, v67
	v_add_u32_e32 v156, -2, v155
	v_cndmask_b32_e32 v67, 0, v67, vcc
	v_cmp_lt_i32_e32 vcc, -1, v156
	v_cvt_f32_i32_e32 v156, v156
	v_cvt_pk_bf16_f32 v66, v66, v67
	v_mul_f32_e32 v156, v151, v156
	v_exp_f32_e32 v156, v156
	s_nop 0
	v_mul_f32_e32 v156, 0x3db504f3, v156
	v_mul_f32_e32 v68, v156, v68
	v_add_u32_e32 v156, -3, v155
	v_cndmask_b32_e32 v68, 0, v68, vcc
	v_cmp_lt_i32_e32 vcc, -1, v156
	v_cvt_f32_i32_e32 v156, v156
	v_mul_f32_e32 v156, v151, v156
	v_exp_f32_e32 v156, v156
	s_nop 0
	v_mul_f32_e32 v156, 0x3db504f3, v156
	v_mul_f32_e32 v69, v156, v69
	v_add_u32_e32 v156, -8, v155
	v_cndmask_b32_e32 v69, 0, v69, vcc
	v_cmp_lt_i32_e32 vcc, -1, v156
	v_cvt_f32_i32_e32 v156, v156
	v_cvt_pk_bf16_f32 v67, v68, v69
	v_mul_f32_e32 v156, v151, v156
	v_exp_f32_e32 v156, v156
	s_nop 0
	v_mul_f32_e32 v156, 0x3db504f3, v156
	v_mul_f32_e32 v70, v156, v70
	v_add_u32_e32 v156, -9, v155
	v_cndmask_b32_e32 v70, 0, v70, vcc
	v_cmp_lt_i32_e32 vcc, -1, v156
	v_cvt_f32_i32_e32 v156, v156
	v_mul_f32_e32 v156, v151, v156
	v_exp_f32_e32 v156, v156
	s_nop 0
	v_mul_f32_e32 v156, 0x3db504f3, v156
	v_mul_f32_e32 v71, v156, v71
	v_add_u32_e32 v156, -10, v155
	v_cndmask_b32_e32 v71, 0, v71, vcc
	v_cmp_lt_i32_e32 vcc, -1, v156
	v_cvt_f32_i32_e32 v156, v156
	v_cvt_pk_bf16_f32 v68, v70, v71
	v_mul_f32_e32 v156, v151, v156
	v_exp_f32_e32 v156, v156
	s_nop 0
	v_mul_f32_e32 v156, 0x3db504f3, v156
	v_mul_f32_e32 v72, v156, v72
	v_add_u32_e32 v156, -11, v155
	v_cndmask_b32_e32 v72, 0, v72, vcc
	v_cmp_lt_i32_e32 vcc, -1, v156
	v_cvt_f32_i32_e32 v156, v156
	v_mul_f32_e32 v156, v151, v156
	v_exp_f32_e32 v156, v156
	s_nop 0
	v_mul_f32_e32 v156, 0x3db504f3, v156
	v_mul_f32_e32 v73, v156, v73
	v_add_u32_e32 v156, -16, v155
	v_cndmask_b32_e32 v73, 0, v73, vcc
	v_cmp_lt_i32_e32 vcc, -1, v156
	v_cvt_f32_i32_e32 v156, v156
	v_cvt_pk_bf16_f32 v69, v72, v73
	v_mul_f32_e32 v156, v151, v156
	v_exp_f32_e32 v156, v156
	s_nop 0
	v_mul_f32_e32 v156, 0x3db504f3, v156
	v_mul_f32_e32 v74, v156, v74
	v_subrev_u32_e32 v156, 17, v155
	v_cndmask_b32_e32 v74, 0, v74, vcc
	v_cmp_lt_i32_e32 vcc, -1, v156
	v_cvt_f32_i32_e32 v156, v156
	v_mul_f32_e32 v156, v151, v156
	v_exp_f32_e32 v156, v156
	s_nop 0
	v_mul_f32_e32 v156, 0x3db504f3, v156
	v_mul_f32_e32 v75, v156, v75
	v_subrev_u32_e32 v156, 18, v155
	v_cndmask_b32_e32 v75, 0, v75, vcc
	v_cmp_lt_i32_e32 vcc, -1, v156
	v_cvt_f32_i32_e32 v156, v156
	v_mul_f32_e32 v156, v151, v156
	v_exp_f32_e32 v156, v156
	s_nop 0
	v_mul_f32_e32 v156, 0x3db504f3, v156
	v_mul_f32_e32 v76, v156, v76
	v_subrev_u32_e32 v156, 19, v155
	v_cndmask_b32_e32 v76, 0, v76, vcc
	v_cmp_lt_i32_e32 vcc, -1, v156
	v_cvt_f32_i32_e32 v156, v156
	v_mul_f32_e32 v156, v151, v156
	v_exp_f32_e32 v156, v156
	s_nop 0
	v_mul_f32_e32 v156, 0x3db504f3, v156
	v_mul_f32_e32 v77, v156, v77
	v_subrev_u32_e32 v156, 24, v155
	v_cndmask_b32_e32 v77, 0, v77, vcc
	v_cmp_lt_i32_e32 vcc, -1, v156
	v_cvt_f32_i32_e32 v156, v156
	v_mul_f32_e32 v156, v151, v156
	v_exp_f32_e32 v156, v156
	s_nop 0
	v_mul_f32_e32 v156, 0x3db504f3, v156
	v_mul_f32_e32 v78, v156, v78
	v_subrev_u32_e32 v156, 25, v155
	v_cndmask_b32_e32 v78, 0, v78, vcc
	v_cmp_lt_i32_e32 vcc, -1, v156
	v_cvt_f32_i32_e32 v156, v156
	v_mul_f32_e32 v156, v151, v156
	v_exp_f32_e32 v156, v156
	s_nop 0
	v_mul_f32_e32 v156, 0x3db504f3, v156
	v_mul_f32_e32 v79, v156, v79
	v_subrev_u32_e32 v156, 26, v155
	v_cndmask_b32_e32 v79, 0, v79, vcc
	v_cmp_lt_i32_e32 vcc, -1, v156
	v_cvt_f32_i32_e32 v156, v156
	v_subrev_u32_e32 v155, 27, v155
	v_mul_f32_e32 v156, v151, v156
	v_exp_f32_e32 v156, v156
	s_nop 0
	v_mul_f32_e32 v156, 0x3db504f3, v156
	v_mul_f32_e32 v80, v156, v80
	v_cndmask_b32_e32 v80, 0, v80, vcc
	v_cmp_lt_i32_e32 vcc, -1, v155
	v_cvt_f32_i32_e32 v155, v155
	v_mul_f32_e32 v155, v151, v155
	v_exp_f32_e32 v155, v155
	s_nop 0
	v_mul_f32_e32 v155, 0x3db504f3, v155
	v_mul_f32_e32 v81, v155, v81
	v_add_u32_e32 v155, s2, v153
	s_waitcnt lgkmcnt(0)
; #define LAS __attribute__((address_space(3)))
; #define MFMA32(a, b, c) __builtin_amdgcn_mfma_f32_32x32x16_bf16((a), (b), (c), 0, 0, 0)
; __device__ __forceinline__ s16x4 tr_read(const LAS unsigned char* p) { return __builtin_bit_cast(s16x4, __builtin_amdgcn_ds_read_tr16_b64_v4i16((LAS s16x4*)p)); }
; __device__ __forceinline__ bf16x8 cat8(s16x4 lo, s16x4 hi) { return __builtin_shufflevector(lo, hi, 0, 1, 2, 3, 4, 5, 6, 7); }
; __device__ __forceinline__ void main_unit(LAS unsigned char* lds, const bf16_t* __restrict__ proj, const bf16_t* __restrict__ sprevT, bf16_t* __restrict__ y,
;                                           const float* __restrict__ rnorm, int b, int h, int n) {
;     ...
; #pragma unroll
;         for (int s2 = 0; s2 < 2; ++s2) {
;             const bf16x8 pb = pack_step(st, s2);
;             const LAS unsigned char* vp = va + (jt * 32 + 16 * s2) * VSTR;
; #pragma unroll
;             for (int t = 0; t < 4; ++t) { const bf16x8 a = cat8(tr_read(vp + t * 64), tr_read(vp + 8 * VSTR + t * 64)); acc[t] = MFMA32(a, pb, acc[t]); }
;         }
;     }
;     float ss = 0.f;
; #pragma unroll
;     for (int t = 0; t < 4; ++t)
; #pragma unroll
;         for (int i = 0; i < 16; ++i) ss += acc[t][i] * acc[t][i];
;     ss += __shfl_xor(ss, 32);
;     LAS float* SS = (LAS float*)(lds + M_SS);
;     if (hh == 0) SS[dh * 128 + iloc] = ss;
;     __syncthreads();
;     const float rstd = __builtin_amdgcn_rsqf((SS[iloc] + SS[128 + iloc]) * (1.0f / 256.0f) + EPS);
;     LAS float* T = (LAS float*)(lds + M_T);
; #pragma unroll
;     for (int t = 0; t < 4; ++t)
; #pragma unroll
;         for (int gq = 0; gq < 4; ++gq) {
;             const f32x4 v = (f32x4){acc[t][4 * gq] * rstd, acc[t][4 * gq + 1] * rstd, acc[t][4 * gq + 2] * rstd, acc[t][4 * gq + 3] * rstd};
;             *(LAS f32x4*)(T + iloc * TSTR + dh * 128 + t * 32 + 8 * gq + 4 * hh) = v;
;         }
;     __syncthreads();
	v_mfma_f32_32x32x16_bf16 v[50:65], v[218:221], v[66:69], v[50:65]
	v_cndmask_b32_e32 v81, 0, v81, vcc
	s_addk_i32 s2, 0x4800
	s_cmp_lg_u32 s3, s2
	s_waitcnt lgkmcnt(0)
	v_mfma_f32_32x32x16_bf16 v[34:49], v[222:225], v[66:69], v[34:49]
	s_waitcnt lgkmcnt(0)
	v_mfma_f32_32x32x16_bf16 v[18:33], v[226:229], v[66:69], v[18:33]
	s_waitcnt lgkmcnt(0)
	v_mfma_f32_32x32x16_bf16 v[2:17], v[230:233], v[66:69], v[2:17]
	v_cvt_pk_bf16_f32 v66, v74, v75
	v_cvt_pk_bf16_f32 v67, v76, v77
	v_cvt_pk_bf16_f32 v68, v78, v79
	v_cvt_pk_bf16_f32 v69, v80, v81
	s_waitcnt lgkmcnt(0)
	v_mfma_f32_32x32x16_bf16 v[50:65], v[234:237], v[66:69], v[50:65]
	s_waitcnt lgkmcnt(0)
	v_mfma_f32_32x32x16_bf16 v[34:49], v[238:241], v[66:69], v[34:49]
	s_waitcnt lgkmcnt(0)
	v_mfma_f32_32x32x16_bf16 v[18:33], v[242:245], v[66:69], v[18:33]
	s_waitcnt lgkmcnt(0)
	v_mfma_f32_32x32x16_bf16 v[2:17], v[246:249], v[66:69], v[2:17]
	s_cbranch_scc1 .LBB0_392
	v_mul_f32_e32 v0, v51, v51
	v_fmac_f32_e32 v0, v50, v50
	v_fmac_f32_e32 v0, v52, v52
	v_fmac_f32_e32 v0, v53, v53
	v_fmac_f32_e32 v0, v54, v54
	v_fmac_f32_e32 v0, v55, v55
	v_fmac_f32_e32 v0, v56, v56
	v_fmac_f32_e32 v0, v57, v57
	v_fmac_f32_e32 v0, v58, v58
	v_fmac_f32_e32 v0, v59, v59
	v_fmac_f32_e32 v0, v60, v60
	v_fmac_f32_e32 v0, v61, v61
	v_fmac_f32_e32 v0, v62, v62
	v_fmac_f32_e32 v0, v63, v63
	v_fmac_f32_e32 v0, v64, v64
	v_fmac_f32_e32 v0, v65, v65
	v_fmac_f32_e32 v0, v34, v34
	v_fmac_f32_e32 v0, v35, v35
	v_fmac_f32_e32 v0, v36, v36
	v_fmac_f32_e32 v0, v37, v37
	v_fmac_f32_e32 v0, v38, v38
	v_fmac_f32_e32 v0, v39, v39
	v_fmac_f32_e32 v0, v40, v40
	v_fmac_f32_e32 v0, v41, v41
	v_fmac_f32_e32 v0, v42, v42
	v_fmac_f32_e32 v0, v43, v43
	v_fmac_f32_e32 v0, v44, v44
	v_fmac_f32_e32 v0, v45, v45
	v_fmac_f32_e32 v0, v46, v46
	v_fmac_f32_e32 v0, v47, v47
	v_fmac_f32_e32 v0, v48, v48
	v_fmac_f32_e32 v0, v49, v49
	v_fmac_f32_e32 v0, v18, v18
	v_fmac_f32_e32 v0, v19, v19
	v_fmac_f32_e32 v0, v20, v20
	v_fmac_f32_e32 v0, v21, v21
	v_fmac_f32_e32 v0, v22, v22
	v_fmac_f32_e32 v0, v23, v23
	v_fmac_f32_e32 v0, v24, v24
	v_fmac_f32_e32 v0, v25, v25
	v_fmac_f32_e32 v0, v26, v26
	v_fmac_f32_e32 v0, v27, v27
	v_fmac_f32_e32 v0, v28, v28
	v_fmac_f32_e32 v0, v29, v29
	v_fmac_f32_e32 v0, v30, v30
	v_fmac_f32_e32 v0, v31, v31
	v_fmac_f32_e32 v0, v32, v32
	v_fmac_f32_e32 v0, v33, v33
	v_fmac_f32_e32 v0, v2, v2
	v_fmac_f32_e32 v0, v3, v3
	v_fmac_f32_e32 v0, v4, v4
	v_fmac_f32_e32 v0, v5, v5
	v_fmac_f32_e32 v0, v6, v6
	v_fmac_f32_e32 v0, v7, v7
	v_fmac_f32_e32 v0, v8, v8
	v_fmac_f32_e32 v0, v9, v9
	v_fmac_f32_e32 v0, v10, v10
	v_fmac_f32_e32 v0, v11, v11
	v_fmac_f32_e32 v0, v12, v12
	v_fmac_f32_e32 v0, v13, v13
	v_fmac_f32_e32 v0, v14, v14
	v_fmac_f32_e32 v0, v15, v15
	v_fmac_f32_e32 v0, v16, v16
	v_fmac_f32_e32 v0, v17, v17
	ds_bpermute_b32 v66, v215, v0
	v_cmp_eq_u32_e32 vcc, 0, v148
	s_and_saveexec_b64 s[16:17], vcc
	s_cbranch_execz .LBB0_395
	s_lshl_b32 s2, s1, 2
	s_add_i32 s2, s2, 0
	s_waitcnt lgkmcnt(0)
	v_add_f32_e32 v0, v0, v66
	v_lshl_add_u32 v66, v145, 2, s2
	v_add_u32_e32 v66, 0x20800, v66
	ds_write_b32 v66, v0
.LBB0_395:
	s_or_b64 exec, exec, s[16:17]
	v_lshl_add_u32 v0, v145, 2, 0
	v_add_u32_e32 v0, 0x20800, v0
	s_waitcnt lgkmcnt(0)
	s_barrier
	ds_read2st64_b32 v[66:67], v0 offset1:2
	s_lshl_b32 s1, s1, 2
	v_mul_u32_u24_e32 v68, 0x410, v145
	s_add_i32 s1, s1, 0
	s_lshl_b32 s8, s14, 1
	s_waitcnt lgkmcnt(0)
	v_add_f32_e32 v0, v66, v67
	v_fmamk_f32 v0, v0, 0x3b800000, v209
	v_rsq_f32_e32 v0, v0
	v_lshlrev_b32_e32 v66, 2, v152
	v_add3_u32 v66, s1, v68, v66
	s_movk_i32 s1, 0x410
	v_pk_mul_f32 v[50:51], v[50:51], v[0:1] op_sel_hi:[1,0]
	v_pk_mul_f32 v[52:53], v[52:53], v[0:1] op_sel_hi:[1,0]
	v_pk_mul_f32 v[34:35], v[34:35], v[0:1] op_sel_hi:[1,0]
	v_pk_mul_f32 v[36:37], v[36:37], v[0:1] op_sel_hi:[1,0]
	v_pk_mul_f32 v[18:19], v[18:19], v[0:1] op_sel_hi:[1,0]
	v_pk_mul_f32 v[20:21], v[20:21], v[0:1] op_sel_hi:[1,0]
	v_pk_mul_f32 v[2:3], v[2:3], v[0:1] op_sel_hi:[1,0]
	v_pk_mul_f32 v[4:5], v[4:5], v[0:1] op_sel_hi:[1,0]
	ds_write_b128 v66, v[50:53]
	v_pk_mul_f32 v[50:51], v[54:55], v[0:1] op_sel_hi:[1,0]
	v_pk_mul_f32 v[52:53], v[56:57], v[0:1] op_sel_hi:[1,0]
	ds_write_b128 v66, v[34:37] offset:128
	v_pk_mul_f32 v[34:35], v[38:39], v[0:1] op_sel_hi:[1,0]
	v_pk_mul_f32 v[36:37], v[40:41], v[0:1] op_sel_hi:[1,0]
	ds_write_b128 v66, v[18:21] offset:256
	v_pk_mul_f32 v[18:19], v[22:23], v[0:1] op_sel_hi:[1,0]
	v_pk_mul_f32 v[20:21], v[24:25], v[0:1] op_sel_hi:[1,0]
	ds_write_b128 v66, v[2:5] offset:384
	v_pk_mul_f32 v[2:3], v[6:7], v[0:1] op_sel_hi:[1,0]
	v_pk_mul_f32 v[4:5], v[8:9], v[0:1] op_sel_hi:[1,0]
	ds_write_b128 v66, v[50:53] offset:32
	v_pk_mul_f32 v[50:51], v[58:59], v[0:1] op_sel_hi:[1,0]
	v_pk_mul_f32 v[52:53], v[60:61], v[0:1] op_sel_hi:[1,0]
	ds_write_b128 v66, v[34:37] offset:160
	v_pk_mul_f32 v[34:35], v[42:43], v[0:1] op_sel_hi:[1,0]
	v_pk_mul_f32 v[36:37], v[44:45], v[0:1] op_sel_hi:[1,0]
	ds_write_b128 v66, v[18:21] offset:288
	v_pk_mul_f32 v[18:19], v[26:27], v[0:1] op_sel_hi:[1,0]
	v_pk_mul_f32 v[20:21], v[28:29], v[0:1] op_sel_hi:[1,0]
	ds_write_b128 v66, v[2:5] offset:416
	v_pk_mul_f32 v[2:3], v[10:11], v[0:1] op_sel_hi:[1,0]
	v_pk_mul_f32 v[4:5], v[12:13], v[0:1] op_sel_hi:[1,0]
	ds_write_b128 v66, v[50:53] offset:64
	v_pk_mul_f32 v[50:51], v[62:63], v[0:1] op_sel_hi:[1,0]
	v_pk_mul_f32 v[52:53], v[64:65], v[0:1] op_sel_hi:[1,0]
	ds_write_b128 v66, v[34:37] offset:192
	v_pk_mul_f32 v[34:35], v[46:47], v[0:1] op_sel_hi:[1,0]
	v_pk_mul_f32 v[36:37], v[48:49], v[0:1] op_sel_hi:[1,0]
	ds_write_b128 v66, v[18:21] offset:320
	v_pk_mul_f32 v[18:19], v[30:31], v[0:1] op_sel_hi:[1,0]
	v_pk_mul_f32 v[20:21], v[32:33], v[0:1] op_sel_hi:[1,0]
	ds_write_b128 v66, v[2:5] offset:448
	v_pk_mul_f32 v[2:3], v[14:15], v[0:1] op_sel_hi:[1,0]
	v_pk_mul_f32 v[4:5], v[16:17], v[0:1] op_sel_hi:[1,0]
	v_and_b32_e32 v0, 0xf8, v150
	v_lshlrev_b32_e32 v16, 2, v0
	v_lshl_add_u64 v[10:11], v[146:147], 0, s[8:9]
	v_lshlrev_b32_e32 v0, 1, v0
	v_lshl_add_u64 v[10:11], v[10:11], 0, v[0:1]
	v_add_co_u32_e32 v10, vcc, s68, v10
	ds_write_b128 v66, v[50:53] offset:96
	s_nop 0
	v_addc_co_u32_e32 v11, vcc, 0, v11, vcc
	ds_write_b128 v66, v[34:37] offset:224
	ds_write_b128 v66, v[18:21] offset:352
	ds_write_b128 v66, v[2:5] offset:480
	s_waitcnt lgkmcnt(0)
	s_barrier
; #define LAS __attribute__((address_space(3)))
; __device__ __forceinline__ unsigned cvt_pk_bf16(float lo, float hi) { unsigned r; asm volatile("v_cvt_pk_bf16_f32 %0, %1, %2" : "=v"(r) : "v"(lo), "v"(hi)); return r; }
; __device__ __forceinline__ float bf_lo(unsigned w) { return __uint_as_float(w << 16); }
; __device__ __forceinline__ float bf_hi(unsigned w) { return __uint_as_float(w & 0xffff0000u); }
; __device__ __forceinline__ void main_unit(LAS unsigned char* lds, const bf16_t* __restrict__ proj, const bf16_t* __restrict__ sprevT, bf16_t* __restrict__ y,
;                                           const float* __restrict__ rnorm, int b, int h, int n) {
;     ...
;     { const int c = tid & 31;
;       const f32x4 w0 = *(const f32x4*)(rnorm + c * 8), w1 = *(const f32x4*)(rnorm + c * 8 + 4);
; #pragma unroll
;       for (int p = 0; p < 8; ++p) {
;           const int row = (tid >> 5) + 16 * p;
;           const f32x4 v0 = *(const LAS f32x4*)(T + row * TSTR + c * 8) * w0, v1 = *(const LAS f32x4*)(T + row * TSTR + c * 8 + 4) * w1;
;           const u32x4 gg = *(const u32x4*)(proj + (row0 + row) * DIN + C_RG + h * 256 + c * 8);
;           float o[8];
; #pragma unroll
;           for (int k = 0; k < 4; ++k) {
;               const float gl = bf_lo(gg[k]), gh = bf_hi(gg[k]);
;               const float vl = k < 2 ? v0[2 * k] : v1[2 * k - 4], vh = k < 2 ? v0[2 * k + 1] : v1[2 * k - 3];
;               o[2 * k] = vl * gl * __builtin_amdgcn_rcpf(1.0f + __builtin_amdgcn_exp2f(-gl * LOG2E));
;               o[2 * k + 1] = vh * gh * __builtin_amdgcn_rcpf(1.0f + __builtin_amdgcn_exp2f(-gh * LOG2E));
;           }
;           u32x4 w; w.x = cvt_pk_bf16(o[0], o[1]); w.y = cvt_pk_bf16(o[2], o[3]); w.z = cvt_pk_bf16(o[4], o[5]); w.w = cvt_pk_bf16(o[6], o[7]);
;           *(u32x4*)(y + (row0 + row) * DM + 1024 + h * 256 + c * 8) = w;
;       } }
	global_load_dwordx4 v[6:9], v16, s[62:63] offset:16
	global_load_dwordx4 v[2:5], v16, s[62:63]
	global_load_dwordx4 v[12:15], v[10:11], off offset:2048
	v_add_co_u32_e32 v250, vcc, 0x30000, v10
	s_nop 1
	v_addc_co_u32_e32 v251, vcc, 0, v11, vcc
	global_load_dwordx4 v[218:221], v[250:251], off offset:2048
	v_add_co_u32_e32 v250, vcc, 0x60000, v10
	s_nop 1
	v_addc_co_u32_e32 v251, vcc, 0, v11, vcc
	global_load_dwordx4 v[222:225], v[250:251], off offset:2048
	v_add_co_u32_e32 v250, vcc, 0x90000, v10
	s_nop 1
	v_addc_co_u32_e32 v251, vcc, 0, v11, vcc
	global_load_dwordx4 v[226:229], v[250:251], off offset:2048
	v_add_co_u32_e32 v250, vcc, 0xc0000, v10
	s_nop 1
	v_addc_co_u32_e32 v251, vcc, 0, v11, vcc
	global_load_dwordx4 v[230:233], v[250:251], off offset:2048
	v_add_co_u32_e32 v250, vcc, 0xf0000, v10
	s_nop 1
	v_addc_co_u32_e32 v251, vcc, 0, v11, vcc
	global_load_dwordx4 v[234:237], v[250:251], off offset:2048
	v_add_co_u32_e32 v250, vcc, 0x120000, v10
	s_nop 1
	v_addc_co_u32_e32 v251, vcc, 0, v11, vcc
	global_load_dwordx4 v[238:241], v[250:251], off offset:2048
	v_add_co_u32_e32 v250, vcc, 0x150000, v10
	s_nop 1
	v_addc_co_u32_e32 v251, vcc, 0, v11, vcc
	global_load_dwordx4 v[242:245], v[250:251], off offset:2048
	v_mul_lo_u32 v10, v144, s1
	v_add3_u32 v10, 0, v16, v10
	ds_read_b128 v[16:19], v10
	ds_read_b128 v[20:23], v10 offset:16
	v_readlane_b32 s2, v254, 49
	v_readlane_b32 s3, v254, 50
	v_add_u32_e32 v32, 0x4100, v10
	s_mov_b64 s[14:15], 0
	s_waitcnt vmcnt(9) lgkmcnt(0)
	v_pk_mul_f32 v[20:21], v[6:7], v[20:21]
	s_waitcnt vmcnt(8)
	v_pk_mul_f32 v[16:17], v[2:3], v[16:17]
	s_waitcnt vmcnt(7)
	v_lshlrev_b32_e32 v11, 16, v12
	v_mul_f32_e32 v16, v16, v11
	v_mul_f32_e32 v11, 0xbfb8aa3b, v11
	v_exp_f32_e32 v11, v11
	v_and_b32_e32 v12, 0xffff0000, v12
	v_mul_f32_e32 v17, v17, v12
	v_mul_f32_e32 v12, 0xbfb8aa3b, v12
	v_exp_f32_e32 v12, v12
	v_add_f32_e32 v11, 1.0, v11
	v_rcp_f32_e32 v11, v11
	v_lshlrev_b32_e32 v24, 16, v13
	v_and_b32_e32 v13, 0xffff0000, v13
	v_add_f32_e32 v12, 1.0, v12
	v_mul_f32_e32 v26, 0xbfb8aa3b, v13
	v_rcp_f32_e32 v12, v12
	v_mul_f32_e32 v11, v16, v11
	v_exp_f32_e32 v16, v26
	v_pk_mul_f32 v[18:19], v[4:5], v[18:19]
	v_mul_f32_e32 v12, v17, v12
	v_mul_f32_e32 v17, v18, v24
	v_lshlrev_b32_e32 v18, 16, v14
	v_mul_f32_e32 v25, 0xbfb8aa3b, v24
	v_add_f32_e32 v16, 1.0, v16
	v_mul_f32_e32 v24, 0xbfb8aa3b, v18
	v_rcp_f32_e32 v16, v16
	v_exp_f32_e32 v24, v24
	v_mul_f32_e32 v13, v19, v13
	v_and_b32_e32 v14, 0xffff0000, v14
	v_mul_f32_e32 v13, v13, v16
	v_add_f32_e32 v16, 1.0, v24
	v_mul_f32_e32 v19, 0xbfb8aa3b, v14
	v_rcp_f32_e32 v16, v16
	v_exp_f32_e32 v19, v19
	v_exp_f32_e32 v25, v25
	v_mul_f32_e32 v18, v20, v18
	v_mul_f32_e32 v16, v18, v16
	v_add_f32_e32 v18, 1.0, v19
	v_lshlrev_b32_e32 v19, 16, v15
	v_and_b32_e32 v15, 0xffff0000, v15
	v_mul_f32_e32 v14, v21, v14
	v_mul_f32_e32 v20, 0xbfb8aa3b, v19
	v_mul_f32_e32 v21, 0xbfb8aa3b, v15
	v_add_f32_e32 v25, 1.0, v25
	v_rcp_f32_e32 v18, v18
	v_exp_f32_e32 v20, v20
	v_exp_f32_e32 v21, v21
	v_rcp_f32_e32 v25, v25
	v_mul_f32_e32 v14, v14, v18
	v_add_f32_e32 v18, 1.0, v20
	v_add_f32_e32 v20, 1.0, v21
	v_mul_f32_e32 v17, v17, v25
	v_rcp_f32_e32 v18, v18
	v_rcp_f32_e32 v20, v20
	v_cvt_pk_bf16_f32 v12, v11, v12
	v_cvt_pk_bf16_f32 v13, v17, v13
	v_cvt_pk_bf16_f32 v14, v16, v14
	v_lshl_add_u64 v[16:17], v[142:143], 0, s[8:9]
	v_pk_mul_f32 v[22:23], v[8:9], v[22:23]
	v_lshl_add_u64 v[16:17], v[16:17], 0, v[0:1]
	v_mul_f32_e32 v19, v22, v19
	v_mul_f32_e32 v15, v23, v15
	v_add_co_u32_e32 v16, vcc, s68, v16
	v_mul_f32_e32 v18, v19, v18
	v_mul_f32_e32 v15, v15, v20
	v_addc_co_u32_e32 v17, vcc, 0, v17, vcc
	v_cvt_pk_bf16_f32 v15, v18, v15
	v_lshlrev_b64 v[20:21], 12, v[140:141]
	v_lshl_add_u64 v[24:25], s[2:3], 0, v[20:21]
	ds_read_b128 v[20:23], v10 offset:16640
	v_lshl_add_u64 v[28:29], v[24:25], 0, s[8:9]
	ds_read_b128 v[24:27], v10 offset:16656
	v_lshl_add_u64 v[28:29], v[28:29], 0, v[0:1]
	global_store_dwordx4 v[28:29], v[12:15], off offset:2048
	s_waitcnt vmcnt(7)
	v_mov_b32_e32 v16, v218
	v_mov_b32_e32 v17, v219
	v_mov_b32_e32 v18, v220
	v_mov_b32_e32 v19, v221
	v_lshlrev_b32_e32 v11, 16, v16
	s_waitcnt lgkmcnt(1)
	v_pk_mul_f32 v[12:13], v[4:5], v[22:23]
	v_pk_mul_f32 v[14:15], v[2:3], v[20:21]
	s_waitcnt lgkmcnt(0)
	v_pk_mul_f32 v[22:23], v[6:7], v[24:25]
	v_and_b32_e32 v16, 0xffff0000, v16
	v_lshlrev_b32_e32 v24, 16, v17
	v_mul_f32_e32 v14, v14, v11
	v_mul_f32_e32 v11, 0xbfb8aa3b, v11
	v_mul_f32_e32 v15, v15, v16
	v_mul_f32_e32 v16, 0xbfb8aa3b, v16
	v_mul_f32_e32 v12, v12, v24
	v_mul_f32_e32 v24, 0xbfb8aa3b, v24
	v_exp_f32_e32 v11, v11
	v_exp_f32_e32 v16, v16
	v_exp_f32_e32 v24, v24
	v_and_b32_e32 v17, 0xffff0000, v17
	v_mul_f32_e32 v13, v13, v17
	v_mul_f32_e32 v17, 0xbfb8aa3b, v17
	v_exp_f32_e32 v17, v17
	v_add_f32_e32 v11, 1.0, v11
	v_add_f32_e32 v16, 1.0, v16
	v_add_f32_e32 v24, 1.0, v24
	v_rcp_f32_e32 v11, v11
	v_rcp_f32_e32 v16, v16
	v_rcp_f32_e32 v24, v24
	v_lshlrev_b32_e32 v25, 16, v18
	v_and_b32_e32 v18, 0xffff0000, v18
	v_add_f32_e32 v17, 1.0, v17
	v_rcp_f32_e32 v17, v17
	v_mul_f32_e32 v11, v14, v11
	v_mul_f32_e32 v14, v15, v16
	v_mul_f32_e32 v15, v12, v24
	v_mul_f32_e32 v12, 0xbfb8aa3b, v18
	v_exp_f32_e32 v12, v12
	v_mul_f32_e32 v13, v13, v17
	v_mul_f32_e32 v17, v23, v18
	v_lshlrev_b32_e32 v18, 16, v19
	v_pk_mul_f32 v[20:21], v[8:9], v[26:27]
	v_mul_f32_e32 v26, 0xbfb8aa3b, v25
	v_mul_f32_e32 v16, v22, v25
	v_add_f32_e32 v12, 1.0, v12
	v_and_b32_e32 v19, 0xffff0000, v19
	v_mul_f32_e32 v22, 0xbfb8aa3b, v18
	v_exp_f32_e32 v26, v26
	v_rcp_f32_e32 v12, v12
	v_exp_f32_e32 v22, v22
	v_mul_f32_e32 v23, 0xbfb8aa3b, v19
	v_exp_f32_e32 v23, v23
	v_add_f32_e32 v26, 1.0, v26
	v_mul_f32_e32 v17, v17, v12
	v_add_f32_e32 v12, 1.0, v22
	v_rcp_f32_e32 v26, v26
	v_rcp_f32_e32 v12, v12
	v_add_f32_e32 v22, 1.0, v23
	v_rcp_f32_e32 v22, v22
	v_mul_f32_e32 v18, v20, v18
	v_mul_f32_e32 v16, v16, v26
	v_mul_f32_e32 v18, v18, v12
	v_mul_f32_e32 v12, v21, v19
	v_mul_f32_e32 v19, v12, v22
	v_cvt_pk_bf16_f32 v12, v11, v14
	v_cvt_pk_bf16_f32 v13, v15, v13
	v_cvt_pk_bf16_f32 v14, v16, v17
	v_lshl_add_u64 v[16:17], v[138:139], 0, s[8:9]
	v_lshl_add_u64 v[16:17], v[16:17], 0, v[0:1]
	v_add_co_u32_e32 v16, vcc, s68, v16
	v_cvt_pk_bf16_f32 v15, v18, v19
	v_lshlrev_b64 v[20:21], 12, v[136:137]
	s_nop 0
	v_addc_co_u32_e32 v17, vcc, 0, v17, vcc
	v_lshl_add_u64 v[24:25], s[2:3], 0, v[20:21]
	ds_read_b128 v[20:23], v10 offset:33280
	v_lshl_add_u64 v[28:29], v[24:25], 0, s[8:9]
	ds_read_b128 v[24:27], v10 offset:33296
	v_lshl_add_u64 v[28:29], v[28:29], 0, v[0:1]
	global_store_dwordx4 v[28:29], v[12:15], off offset:2048
	s_waitcnt vmcnt(7)
; #define LAS __attribute__((address_space(3)))
; __device__ __forceinline__ unsigned cvt_pk_bf16(float lo, float hi) { unsigned r; asm volatile("v_cvt_pk_bf16_f32 %0, %1, %2" : "=v"(r) : "v"(lo), "v"(hi)); return r; }
; __device__ __forceinline__ float bf_lo(unsigned w) { return __uint_as_float(w << 16); }
; __device__ __forceinline__ float bf_hi(unsigned w) { return __uint_as_float(w & 0xffff0000u); }
; __device__ __forceinline__ void main_unit(LAS unsigned char* lds, const bf16_t* __restrict__ proj, const bf16_t* __restrict__ sprevT, bf16_t* __restrict__ y,
;                                           const float* __restrict__ rnorm, int b, int h, int n) {
;     ...
;       for (int p = 0; p < 8; ++p) {
;           const int row = (tid >> 5) + 16 * p;
;           const f32x4 v0 = *(const LAS f32x4*)(T + row * TSTR + c * 8) * w0, v1 = *(const LAS f32x4*)(T + row * TSTR + c * 8 + 4) * w1;
;           const u32x4 gg = *(const u32x4*)(proj + (row0 + row) * DIN + C_RG + h * 256 + c * 8);
;           float o[8];
; #pragma unroll
;           for (int k = 0; k < 4; ++k) {
;               const float gl = bf_lo(gg[k]), gh = bf_hi(gg[k]);
;               const float vl = k < 2 ? v0[2 * k] : v1[2 * k - 4], vh = k < 2 ? v0[2 * k + 1] : v1[2 * k - 3];
;               o[2 * k] = vl * gl * __builtin_amdgcn_rcpf(1.0f + __builtin_amdgcn_exp2f(-gl * LOG2E));
;               o[2 * k + 1] = vh * gh * __builtin_amdgcn_rcpf(1.0f + __builtin_amdgcn_exp2f(-gh * LOG2E));
;           }
;           u32x4 w; w.x = cvt_pk_bf16(o[0], o[1]); w.y = cvt_pk_bf16(o[2], o[3]); w.z = cvt_pk_bf16(o[4], o[5]); w.w = cvt_pk_bf16(o[6], o[7]);
;           *(u32x4*)(y + (row0 + row) * DM + 1024 + h * 256 + c * 8) = w;
	v_mov_b32_e32 v16, v222
	v_mov_b32_e32 v17, v223
	v_mov_b32_e32 v18, v224
	v_mov_b32_e32 v19, v225
	v_lshlrev_b32_e32 v11, 16, v16
	s_waitcnt lgkmcnt(1)
	v_pk_mul_f32 v[12:13], v[4:5], v[22:23]
	v_pk_mul_f32 v[14:15], v[2:3], v[20:21]
	s_waitcnt lgkmcnt(0)
	v_pk_mul_f32 v[22:23], v[6:7], v[24:25]
	v_and_b32_e32 v16, 0xffff0000, v16
	v_lshlrev_b32_e32 v24, 16, v17
	v_and_b32_e32 v17, 0xffff0000, v17
	v_lshlrev_b32_e32 v25, 16, v18
	v_and_b32_e32 v18, 0xffff0000, v18
	v_mul_f32_e32 v14, v14, v11
	v_mul_f32_e32 v11, 0xbfb8aa3b, v11
	v_mul_f32_e32 v15, v15, v16
	v_mul_f32_e32 v16, 0xbfb8aa3b, v16
	v_mul_f32_e32 v12, v12, v24
	v_mul_f32_e32 v24, 0xbfb8aa3b, v24
	v_mul_f32_e32 v13, v13, v17
	v_mul_f32_e32 v17, 0xbfb8aa3b, v17
	v_mul_f32_e32 v23, v23, v18
	v_mul_f32_e32 v18, 0xbfb8aa3b, v18
	v_exp_f32_e32 v11, v11
	v_exp_f32_e32 v16, v16
	v_exp_f32_e32 v24, v24
	v_exp_f32_e32 v17, v17
	v_exp_f32_e32 v18, v18
	v_pk_mul_f32 v[20:21], v[8:9], v[26:27]
	v_lshlrev_b32_e32 v26, 16, v19
	v_and_b32_e32 v19, 0xffff0000, v19
	v_mul_f32_e32 v22, v22, v25
	v_mul_f32_e32 v25, 0xbfb8aa3b, v25
	v_mul_f32_e32 v27, 0xbfb8aa3b, v26
	v_add_f32_e32 v11, 1.0, v11
	v_add_f32_e32 v16, 1.0, v16
	v_add_f32_e32 v24, 1.0, v24
	v_mul_f32_e32 v28, 0xbfb8aa3b, v19
	v_exp_f32_e32 v25, v25
	v_exp_f32_e32 v27, v27
	v_add_f32_e32 v17, 1.0, v17
	v_add_f32_e32 v18, 1.0, v18
	v_rcp_f32_e32 v11, v11
	v_rcp_f32_e32 v16, v16
	v_rcp_f32_e32 v24, v24
	v_exp_f32_e32 v28, v28
	v_rcp_f32_e32 v17, v17
	v_rcp_f32_e32 v18, v18
	v_add_f32_e32 v25, 1.0, v25
	v_mul_f32_e32 v11, v14, v11
	v_mul_f32_e32 v14, v15, v16
	v_mul_f32_e32 v15, v12, v24
	v_add_f32_e32 v12, 1.0, v27
	v_rcp_f32_e32 v25, v25
	v_mul_f32_e32 v13, v13, v17
	v_mul_f32_e32 v17, v23, v18
	v_rcp_f32_e32 v12, v12
	v_add_f32_e32 v18, 1.0, v28
	v_rcp_f32_e32 v18, v18
	v_mul_f32_e32 v20, v20, v26
	v_mul_f32_e32 v16, v22, v25
	v_mul_f32_e32 v20, v20, v12
	v_mul_f32_e32 v12, v21, v19
	v_mul_f32_e32 v18, v12, v18
	v_cvt_pk_bf16_f32 v12, v11, v14
	v_cvt_pk_bf16_f32 v13, v15, v13
	v_cvt_pk_bf16_f32 v14, v16, v17
	v_lshl_add_u64 v[16:17], v[134:135], 0, s[8:9]
	v_lshl_add_u64 v[16:17], v[16:17], 0, v[0:1]
	v_add_co_u32_e32 v16, vcc, s68, v16
	v_cvt_pk_bf16_f32 v15, v20, v18
	v_lshlrev_b64 v[20:21], 12, v[132:133]
	s_nop 0
	v_addc_co_u32_e32 v17, vcc, 0, v17, vcc
	v_lshl_add_u64 v[20:21], s[2:3], 0, v[20:21]
	v_lshl_add_u64 v[24:25], v[130:131], 0, s[8:9]
	v_lshl_add_u64 v[28:29], v[20:21], 0, s[8:9]
	ds_read_b128 v[20:23], v10 offset:49920
	v_lshl_add_u64 v[30:31], v[24:25], 0, v[0:1]
	ds_read_b128 v[24:27], v10 offset:49936
	v_lshl_add_u64 v[28:29], v[28:29], 0, v[0:1]
	global_store_dwordx4 v[28:29], v[12:15], off offset:2048
	s_waitcnt vmcnt(7)
	v_mov_b32_e32 v16, v226
	v_mov_b32_e32 v17, v227
	v_mov_b32_e32 v18, v228
	v_mov_b32_e32 v19, v229
	v_lshlrev_b32_e32 v11, 16, v16
	s_waitcnt lgkmcnt(1)
	v_pk_mul_f32 v[12:13], v[4:5], v[22:23]
	v_pk_mul_f32 v[14:15], v[2:3], v[20:21]
	s_waitcnt lgkmcnt(0)
	v_pk_mul_f32 v[22:23], v[6:7], v[24:25]
	v_and_b32_e32 v16, 0xffff0000, v16
	v_lshlrev_b32_e32 v24, 16, v17
	v_and_b32_e32 v17, 0xffff0000, v17
	v_lshlrev_b32_e32 v25, 16, v18
	v_and_b32_e32 v18, 0xffff0000, v18
	v_mul_f32_e32 v14, v14, v11
	v_mul_f32_e32 v11, 0xbfb8aa3b, v11
	v_mul_f32_e32 v15, v15, v16
	v_mul_f32_e32 v16, 0xbfb8aa3b, v16
	v_mul_f32_e32 v13, v13, v17
	v_mul_f32_e32 v17, 0xbfb8aa3b, v17
	v_mul_f32_e32 v22, v22, v25
	v_mul_f32_e32 v25, 0xbfb8aa3b, v25
	v_pk_mul_f32 v[20:21], v[8:9], v[26:27]
	v_lshlrev_b32_e32 v26, 16, v19
	v_and_b32_e32 v19, 0xffff0000, v19
	v_mul_f32_e32 v12, v12, v24
	v_mul_f32_e32 v24, 0xbfb8aa3b, v24
	v_mul_f32_e32 v23, v23, v18
	v_mul_f32_e32 v18, 0xbfb8aa3b, v18
	v_exp_f32_e32 v11, v11
	v_exp_f32_e32 v16, v16
	v_exp_f32_e32 v17, v17
	v_exp_f32_e32 v25, v25
	v_mul_f32_e32 v20, v20, v26
	v_mul_f32_e32 v26, 0xbfb8aa3b, v26
	v_mul_f32_e32 v21, v21, v19
	v_mul_f32_e32 v19, 0xbfb8aa3b, v19
	v_exp_f32_e32 v24, v24
	v_exp_f32_e32 v18, v18
	v_exp_f32_e32 v26, v26
	v_exp_f32_e32 v19, v19
	v_add_f32_e32 v11, 1.0, v11
	v_add_f32_e32 v16, 1.0, v16
	v_add_f32_e32 v17, 1.0, v17
	v_add_f32_e32 v25, 1.0, v25
	v_add_f32_e32 v24, 1.0, v24
	v_add_f32_e32 v18, 1.0, v18
	v_rcp_f32_e32 v11, v11
	v_rcp_f32_e32 v16, v16
	v_rcp_f32_e32 v17, v17
	v_rcp_f32_e32 v25, v25
	v_add_f32_e32 v26, 1.0, v26
	v_add_f32_e32 v19, 1.0, v19
	v_rcp_f32_e32 v24, v24
	v_rcp_f32_e32 v18, v18
	v_rcp_f32_e32 v26, v26
	v_rcp_f32_e32 v19, v19
	v_mul_f32_e32 v11, v14, v11
	v_mul_f32_e32 v14, v15, v16
	v_mul_f32_e32 v13, v13, v17
	v_mul_f32_e32 v16, v22, v25
	v_mul_f32_e32 v15, v12, v24
	v_mul_f32_e32 v17, v23, v18
	v_cvt_pk_bf16_f32 v12, v11, v14
	v_cvt_pk_bf16_f32 v13, v15, v13
	v_cvt_pk_bf16_f32 v14, v16, v17
	v_add_co_u32_e32 v16, vcc, s68, v30
	v_mul_f32_e32 v18, v20, v26
	v_mul_f32_e32 v19, v21, v19
	v_addc_co_u32_e32 v17, vcc, 0, v31, vcc
	v_cvt_pk_bf16_f32 v15, v18, v19
	v_lshlrev_b64 v[20:21], 12, v[128:129]
	v_lshl_add_u64 v[20:21], s[2:3], 0, v[20:21]
	v_lshl_add_u64 v[22:23], v[126:127], 0, s[8:9]
	v_lshl_add_u64 v[20:21], v[20:21], 0, s[8:9]
	v_lshl_add_u64 v[28:29], v[22:23], 0, v[0:1]
	v_lshl_add_u64 v[30:31], v[20:21], 0, v[0:1]
	ds_read_b128 v[20:23], v32 offset:49920
	ds_read_b128 v[24:27], v32 offset:49936
	global_store_dwordx4 v[30:31], v[12:15], off offset:2048
	v_add_co_u32_e32 v28, vcc, s68, v28
	s_waitcnt lgkmcnt(1)
	v_pk_mul_f32 v[12:13], v[4:5], v[22:23]
	v_pk_mul_f32 v[14:15], v[2:3], v[20:21]
	s_waitcnt lgkmcnt(0)
	v_pk_mul_f32 v[20:21], v[8:9], v[26:27]
	v_pk_mul_f32 v[22:23], v[6:7], v[24:25]
	v_addc_co_u32_e32 v29, vcc, 0, v29, vcc
	s_waitcnt vmcnt(7)
; #define LAS __attribute__((address_space(3)))
; __device__ __forceinline__ unsigned cvt_pk_bf16(float lo, float hi) { unsigned r; asm volatile("v_cvt_pk_bf16_f32 %0, %1, %2" : "=v"(r) : "v"(lo), "v"(hi)); return r; }
; __device__ __forceinline__ float bf_lo(unsigned w) { return __uint_as_float(w << 16); }
; __device__ __forceinline__ float bf_hi(unsigned w) { return __uint_as_float(w & 0xffff0000u); }
; __device__ __forceinline__ void main_unit(LAS unsigned char* lds, const bf16_t* __restrict__ proj, const bf16_t* __restrict__ sprevT, bf16_t* __restrict__ y,
;                                           const float* __restrict__ rnorm, int b, int h, int n) {
;     ...
;     { const int c = tid & 31;
;       const f32x4 w0 = *(const f32x4*)(rnorm + c * 8), w1 = *(const f32x4*)(rnorm + c * 8 + 4);
; #pragma unroll
;       for (int p = 0; p < 8; ++p) {
;           const int row = (tid >> 5) + 16 * p;
;           const f32x4 v0 = *(const LAS f32x4*)(T + row * TSTR + c * 8) * w0, v1 = *(const LAS f32x4*)(T + row * TSTR + c * 8 + 4) * w1;
;           const u32x4 gg = *(const u32x4*)(proj + (row0 + row) * DIN + C_RG + h * 256 + c * 8);
;           float o[8];
; #pragma unroll
;           for (int k = 0; k < 4; ++k) {
;               const float gl = bf_lo(gg[k]), gh = bf_hi(gg[k]);
;               const float vl = k < 2 ? v0[2 * k] : v1[2 * k - 4], vh = k < 2 ? v0[2 * k + 1] : v1[2 * k - 3];
;               o[2 * k] = vl * gl * __builtin_amdgcn_rcpf(1.0f + __builtin_amdgcn_exp2f(-gl * LOG2E));
;               o[2 * k + 1] = vh * gh * __builtin_amdgcn_rcpf(1.0f + __builtin_amdgcn_exp2f(-gh * LOG2E));
;           }
;           u32x4 w; w.x = cvt_pk_bf16(o[0], o[1]); w.y = cvt_pk_bf16(o[2], o[3]); w.z = cvt_pk_bf16(o[4], o[5]); w.w = cvt_pk_bf16(o[6], o[7]);
;           *(u32x4*)(y + (row0 + row) * DM + 1024 + h * 256 + c * 8) = w;
	v_mov_b32_e32 v16, v230
	v_mov_b32_e32 v17, v231
	v_mov_b32_e32 v18, v232
	v_mov_b32_e32 v19, v233
	v_lshlrev_b32_e32 v11, 16, v16
	v_and_b32_e32 v16, 0xffff0000, v16
	v_lshlrev_b32_e32 v24, 16, v17
	v_and_b32_e32 v17, 0xffff0000, v17
	v_lshlrev_b32_e32 v25, 16, v18
	v_and_b32_e32 v18, 0xffff0000, v18
	v_lshlrev_b32_e32 v26, 16, v19
	v_and_b32_e32 v19, 0xffff0000, v19
	v_mul_f32_e32 v14, v14, v11
	v_mul_f32_e32 v11, 0xbfb8aa3b, v11
	v_mul_f32_e32 v15, v15, v16
	v_mul_f32_e32 v16, 0xbfb8aa3b, v16
	v_mul_f32_e32 v12, v12, v24
	v_mul_f32_e32 v24, 0xbfb8aa3b, v24
	v_mul_f32_e32 v13, v13, v17
	v_mul_f32_e32 v17, 0xbfb8aa3b, v17
	v_mul_f32_e32 v22, v22, v25
	v_mul_f32_e32 v25, 0xbfb8aa3b, v25
	v_mul_f32_e32 v23, v23, v18
	v_mul_f32_e32 v18, 0xbfb8aa3b, v18
	v_mul_f32_e32 v20, v20, v26
	v_mul_f32_e32 v26, 0xbfb8aa3b, v26
	v_mul_f32_e32 v21, v21, v19
	v_mul_f32_e32 v19, 0xbfb8aa3b, v19
	v_exp_f32_e32 v11, v11
	v_exp_f32_e32 v16, v16
	v_exp_f32_e32 v24, v24
	v_exp_f32_e32 v17, v17
	v_exp_f32_e32 v25, v25
	v_exp_f32_e32 v18, v18
	v_exp_f32_e32 v26, v26
	v_exp_f32_e32 v19, v19
	v_add_f32_e32 v11, 1.0, v11
	v_add_f32_e32 v16, 1.0, v16
	v_add_f32_e32 v24, 1.0, v24
	v_add_f32_e32 v17, 1.0, v17
	v_add_f32_e32 v25, 1.0, v25
	v_add_f32_e32 v18, 1.0, v18
	v_add_f32_e32 v26, 1.0, v26
	v_add_f32_e32 v19, 1.0, v19
	v_rcp_f32_e32 v11, v11
	v_rcp_f32_e32 v16, v16
	v_rcp_f32_e32 v24, v24
	v_rcp_f32_e32 v17, v17
	v_rcp_f32_e32 v25, v25
	v_rcp_f32_e32 v18, v18
	v_rcp_f32_e32 v26, v26
	v_rcp_f32_e32 v19, v19
	v_mul_f32_e32 v11, v14, v11
	v_mul_f32_e32 v14, v15, v16
	v_mul_f32_e32 v15, v12, v24
	v_mul_f32_e32 v13, v13, v17
	v_mul_f32_e32 v16, v22, v25
	v_mul_f32_e32 v17, v23, v18
	v_mul_f32_e32 v18, v20, v26
	v_mul_f32_e32 v19, v21, v19
	v_cvt_pk_bf16_f32 v12, v11, v14
	v_cvt_pk_bf16_f32 v13, v15, v13
	v_cvt_pk_bf16_f32 v14, v16, v17
	v_cvt_pk_bf16_f32 v15, v18, v19
	v_lshlrev_b64 v[20:21], 12, v[124:125]
	v_lshl_add_u64 v[20:21], s[2:3], 0, v[20:21]
	v_lshl_add_u64 v[22:23], v[122:123], 0, s[8:9]
	v_lshl_add_u64 v[20:21], v[20:21], 0, s[8:9]
	v_add_u32_e32 v11, 0x8200, v10
	v_lshl_add_u64 v[28:29], v[22:23], 0, v[0:1]
	v_lshl_add_u64 v[30:31], v[20:21], 0, v[0:1]
	ds_read_b128 v[20:23], v11 offset:49920
	ds_read_b128 v[24:27], v11 offset:49936
	global_store_dwordx4 v[30:31], v[12:15], off offset:2048
	v_add_co_u32_e32 v28, vcc, s68, v28
	s_waitcnt lgkmcnt(1)
	v_pk_mul_f32 v[12:13], v[4:5], v[22:23]
	v_pk_mul_f32 v[14:15], v[2:3], v[20:21]
	s_waitcnt lgkmcnt(0)
	v_pk_mul_f32 v[20:21], v[8:9], v[26:27]
	v_pk_mul_f32 v[22:23], v[6:7], v[24:25]
	v_addc_co_u32_e32 v29, vcc, 0, v29, vcc
	s_waitcnt vmcnt(7)
	v_mov_b32_e32 v16, v234
	v_mov_b32_e32 v17, v235
	v_mov_b32_e32 v18, v236
	v_mov_b32_e32 v19, v237
	v_lshlrev_b32_e32 v11, 16, v16
	v_and_b32_e32 v16, 0xffff0000, v16
	v_lshlrev_b32_e32 v24, 16, v17
	v_and_b32_e32 v17, 0xffff0000, v17
	v_lshlrev_b32_e32 v25, 16, v18
	v_and_b32_e32 v18, 0xffff0000, v18
	v_lshlrev_b32_e32 v26, 16, v19
	v_and_b32_e32 v19, 0xffff0000, v19
	v_mul_f32_e32 v14, v14, v11
	v_mul_f32_e32 v11, 0xbfb8aa3b, v11
	v_mul_f32_e32 v15, v15, v16
	v_mul_f32_e32 v16, 0xbfb8aa3b, v16
	v_mul_f32_e32 v12, v12, v24
	v_mul_f32_e32 v24, 0xbfb8aa3b, v24
	v_mul_f32_e32 v13, v13, v17
	v_mul_f32_e32 v17, 0xbfb8aa3b, v17
	v_mul_f32_e32 v22, v22, v25
	v_mul_f32_e32 v25, 0xbfb8aa3b, v25
	v_mul_f32_e32 v23, v23, v18
	v_mul_f32_e32 v18, 0xbfb8aa3b, v18
	v_mul_f32_e32 v20, v20, v26
	v_mul_f32_e32 v26, 0xbfb8aa3b, v26
	v_mul_f32_e32 v21, v21, v19
	v_mul_f32_e32 v19, 0xbfb8aa3b, v19
	v_exp_f32_e32 v11, v11
	v_exp_f32_e32 v16, v16
	v_exp_f32_e32 v24, v24
	v_exp_f32_e32 v17, v17
	v_exp_f32_e32 v25, v25
	v_exp_f32_e32 v18, v18
	v_exp_f32_e32 v26, v26
	v_exp_f32_e32 v19, v19
	v_add_f32_e32 v11, 1.0, v11
	v_add_f32_e32 v16, 1.0, v16
	v_add_f32_e32 v24, 1.0, v24
	v_add_f32_e32 v17, 1.0, v17
	v_add_f32_e32 v25, 1.0, v25
	v_add_f32_e32 v18, 1.0, v18
	v_add_f32_e32 v26, 1.0, v26
	v_add_f32_e32 v19, 1.0, v19
	v_rcp_f32_e32 v11, v11
	v_rcp_f32_e32 v16, v16
	v_rcp_f32_e32 v24, v24
	v_rcp_f32_e32 v17, v17
	v_rcp_f32_e32 v25, v25
	v_rcp_f32_e32 v18, v18
	v_rcp_f32_e32 v26, v26
	v_rcp_f32_e32 v19, v19
	v_mul_f32_e32 v11, v14, v11
	v_mul_f32_e32 v14, v15, v16
	v_mul_f32_e32 v15, v12, v24
	v_mul_f32_e32 v13, v13, v17
	v_mul_f32_e32 v16, v22, v25
	v_mul_f32_e32 v17, v23, v18
	v_mul_f32_e32 v18, v20, v26
	v_mul_f32_e32 v19, v21, v19
	v_cvt_pk_bf16_f32 v12, v11, v14
	v_cvt_pk_bf16_f32 v13, v15, v13
	v_cvt_pk_bf16_f32 v14, v16, v17
	v_cvt_pk_bf16_f32 v15, v18, v19
	v_lshlrev_b64 v[20:21], 12, v[120:121]
	v_lshl_add_u64 v[20:21], s[2:3], 0, v[20:21]
	v_lshl_add_u64 v[22:23], v[118:119], 0, s[8:9]
	v_lshl_add_u64 v[20:21], v[20:21], 0, s[8:9]
	v_add_u32_e32 v24, 0xc300, v10
	v_lshl_add_u64 v[28:29], v[22:23], 0, v[0:1]
	v_lshl_add_u64 v[10:11], v[20:21], 0, v[0:1]
	ds_read_b128 v[20:23], v24 offset:49920
	ds_read_b128 v[24:27], v24 offset:49936
	global_store_dwordx4 v[10:11], v[12:15], off offset:2048
	v_add_co_u32_e32 v28, vcc, s68, v28
	s_waitcnt lgkmcnt(1)
; #define LAS __attribute__((address_space(3)))
; __device__ __forceinline__ unsigned cvt_pk_bf16(float lo, float hi) { unsigned r; asm volatile("v_cvt_pk_bf16_f32 %0, %1, %2" : "=v"(r) : "v"(lo), "v"(hi)); return r; }
; __device__ __forceinline__ float bf_lo(unsigned w) { return __uint_as_float(w << 16); }
; __device__ __forceinline__ float bf_hi(unsigned w) { return __uint_as_float(w & 0xffff0000u); }
; __device__ __forceinline__ void main_unit(LAS unsigned char* lds, const bf16_t* __restrict__ proj, const bf16_t* __restrict__ sprevT, bf16_t* __restrict__ y,
;                                           const float* __restrict__ rnorm, int b, int h, int n) {
;     ...
;       for (int p = 0; p < 8; ++p) {
;           const int row = (tid >> 5) + 16 * p;
;           const f32x4 v0 = *(const LAS f32x4*)(T + row * TSTR + c * 8) * w0, v1 = *(const LAS f32x4*)(T + row * TSTR + c * 8 + 4) * w1;
;           const u32x4 gg = *(const u32x4*)(proj + (row0 + row) * DIN + C_RG + h * 256 + c * 8);
;           float o[8];
; #pragma unroll
;           for (int k = 0; k < 4; ++k) {
;               const float gl = bf_lo(gg[k]), gh = bf_hi(gg[k]);
;               const float vl = k < 2 ? v0[2 * k] : v1[2 * k - 4], vh = k < 2 ? v0[2 * k + 1] : v1[2 * k - 3];
;               o[2 * k] = vl * gl * __builtin_amdgcn_rcpf(1.0f + __builtin_amdgcn_exp2f(-gl * LOG2E));
;               o[2 * k + 1] = vh * gh * __builtin_amdgcn_rcpf(1.0f + __builtin_amdgcn_exp2f(-gh * LOG2E));
;           }
;           u32x4 w; w.x = cvt_pk_bf16(o[0], o[1]); w.y = cvt_pk_bf16(o[2], o[3]); w.z = cvt_pk_bf16(o[4], o[5]); w.w = cvt_pk_bf16(o[6], o[7]);
;           *(u32x4*)(y + (row0 + row) * DM + 1024 + h * 256 + c * 8) = w;
;       } }
;     __syncthreads();
	v_pk_mul_f32 v[10:11], v[4:5], v[22:23]
	v_pk_mul_f32 v[12:13], v[2:3], v[20:21]
	s_waitcnt lgkmcnt(0)
	v_pk_mul_f32 v[14:15], v[8:9], v[26:27]
	v_pk_mul_f32 v[20:21], v[6:7], v[24:25]
	v_addc_co_u32_e32 v29, vcc, 0, v29, vcc
	s_waitcnt vmcnt(7)
	v_mov_b32_e32 v16, v238
	v_mov_b32_e32 v17, v239
	v_mov_b32_e32 v18, v240
	v_mov_b32_e32 v19, v241
	v_lshlrev_b32_e32 v22, 16, v16
	v_and_b32_e32 v16, 0xffff0000, v16
	v_lshlrev_b32_e32 v23, 16, v17
	v_and_b32_e32 v17, 0xffff0000, v17
	v_lshlrev_b32_e32 v24, 16, v18
	v_lshlrev_b32_e32 v25, 16, v19
	v_and_b32_e32 v19, 0xffff0000, v19
	v_and_b32_e32 v18, 0xffff0000, v18
	v_mul_f32_e32 v12, v12, v22
	v_mul_f32_e32 v22, 0xbfb8aa3b, v22
	v_mul_f32_e32 v13, v13, v16
	v_mul_f32_e32 v16, 0xbfb8aa3b, v16
	v_mul_f32_e32 v10, v10, v23
	v_mul_f32_e32 v23, 0xbfb8aa3b, v23
	v_mul_f32_e32 v11, v11, v17
	v_mul_f32_e32 v17, 0xbfb8aa3b, v17
	v_mul_f32_e32 v20, v20, v24
	v_mul_f32_e32 v24, 0xbfb8aa3b, v24
	v_mul_f32_e32 v14, v14, v25
	v_mul_f32_e32 v25, 0xbfb8aa3b, v25
	v_mul_f32_e32 v15, v15, v19
	v_mul_f32_e32 v19, 0xbfb8aa3b, v19
	v_mul_f32_e32 v21, v21, v18
	v_mul_f32_e32 v18, 0xbfb8aa3b, v18
	v_exp_f32_e32 v22, v22
	v_exp_f32_e32 v16, v16
	v_exp_f32_e32 v23, v23
	v_exp_f32_e32 v17, v17
	v_exp_f32_e32 v24, v24
	v_exp_f32_e32 v25, v25
	v_exp_f32_e32 v19, v19
	v_exp_f32_e32 v18, v18
	v_add_f32_e32 v22, 1.0, v22
	v_add_f32_e32 v16, 1.0, v16
	v_add_f32_e32 v23, 1.0, v23
	v_add_f32_e32 v17, 1.0, v17
	v_add_f32_e32 v24, 1.0, v24
	v_add_f32_e32 v25, 1.0, v25
	v_add_f32_e32 v19, 1.0, v19
	v_add_f32_e32 v18, 1.0, v18
	v_rcp_f32_e32 v22, v22
	v_rcp_f32_e32 v16, v16
	v_rcp_f32_e32 v23, v23
	v_rcp_f32_e32 v17, v17
	v_rcp_f32_e32 v24, v24
	v_rcp_f32_e32 v25, v25
	v_rcp_f32_e32 v19, v19
	v_rcp_f32_e32 v18, v18
	v_mul_f32_e32 v12, v12, v22
	v_mul_f32_e32 v13, v13, v16
	v_mul_f32_e32 v16, v10, v23
	v_mul_f32_e32 v11, v11, v17
	v_mul_f32_e32 v17, v20, v24
	v_mul_f32_e32 v14, v14, v25
	v_mul_f32_e32 v15, v15, v19
	v_mul_f32_e32 v18, v21, v18
	v_cvt_pk_bf16_f32 v10, v12, v13
	v_cvt_pk_bf16_f32 v11, v16, v11
	v_cvt_pk_bf16_f32 v12, v17, v18
	v_cvt_pk_bf16_f32 v13, v14, v15
	v_lshlrev_b64 v[18:19], 12, v[116:117]
	v_lshlrev_b64 v[20:21], 12, v[114:115]
	v_lshl_add_u64 v[18:19], s[2:3], 0, v[18:19]
	v_add_u32_e32 v22, 0xc300, v32
	v_lshl_add_u64 v[26:27], s[2:3], 0, v[20:21]
	v_lshl_add_u64 v[28:29], v[18:19], 0, s[8:9]
	ds_read_b128 v[18:21], v22 offset:49920
	ds_read_b128 v[22:25], v22 offset:49936
	v_lshl_add_u64 v[28:29], v[28:29], 0, v[0:1]
	v_lshl_add_u64 v[26:27], v[26:27], 0, s[8:9]
	global_store_dwordx4 v[28:29], v[10:13], off offset:2048
	s_waitcnt lgkmcnt(1)
	v_pk_mul_f32 v[4:5], v[4:5], v[20:21]
	s_waitcnt lgkmcnt(0)
	v_pk_mul_f32 v[6:7], v[6:7], v[22:23]
	v_pk_mul_f32 v[2:3], v[2:3], v[18:19]
	v_lshl_add_u64 v[26:27], v[26:27], 0, v[0:1]
	v_pk_mul_f32 v[8:9], v[8:9], v[24:25]
	s_waitcnt vmcnt(7)
	v_mov_b32_e32 v14, v242
	v_mov_b32_e32 v15, v243
	v_mov_b32_e32 v16, v244
	v_mov_b32_e32 v17, v245
	v_and_b32_e32 v11, 0xffff0000, v16
	v_lshlrev_b32_e32 v12, 16, v16
	v_and_b32_e32 v13, 0xffff0000, v15
	v_lshlrev_b32_e32 v15, 16, v15
	v_and_b32_e32 v16, 0xffff0000, v14
	v_lshlrev_b32_e32 v14, 16, v14
	v_and_b32_e32 v0, 0xffff0000, v17
	v_lshlrev_b32_e32 v10, 16, v17
	v_mul_f32_e32 v17, 0xbfb8aa3b, v11
	v_mul_f32_e32 v7, v7, v11
	v_mul_f32_e32 v11, 0xbfb8aa3b, v12
	v_mul_f32_e32 v6, v6, v12
	v_mul_f32_e32 v12, 0xbfb8aa3b, v13
	v_mul_f32_e32 v5, v5, v13
	v_mul_f32_e32 v13, 0xbfb8aa3b, v15
	v_mul_f32_e32 v4, v4, v15
	v_mul_f32_e32 v15, 0xbfb8aa3b, v16
	v_mul_f32_e32 v3, v3, v16
	v_mul_f32_e32 v16, 0xbfb8aa3b, v14
	v_mul_f32_e32 v8, v8, v10
	v_mul_f32_e32 v10, 0xbfb8aa3b, v10
	v_mul_f32_e32 v9, v9, v0
	v_mul_f32_e32 v0, 0xbfb8aa3b, v0
	v_exp_f32_e32 v12, v12
	v_exp_f32_e32 v13, v13
	v_exp_f32_e32 v15, v15
	v_exp_f32_e32 v16, v16
	v_mul_f32_e32 v2, v2, v14
	v_exp_f32_e32 v14, v17
	v_exp_f32_e32 v11, v11
	v_exp_f32_e32 v10, v10
	v_exp_f32_e32 v0, v0
	v_add_f32_e32 v12, 1.0, v12
	v_add_f32_e32 v13, 1.0, v13
	v_add_f32_e32 v15, 1.0, v15
	v_add_f32_e32 v16, 1.0, v16
	v_add_f32_e32 v14, 1.0, v14
	v_add_f32_e32 v11, 1.0, v11
	v_add_f32_e32 v10, 1.0, v10
	v_add_f32_e32 v0, 1.0, v0
	v_rcp_f32_e32 v12, v12
	v_rcp_f32_e32 v13, v13
	v_rcp_f32_e32 v15, v15
	v_rcp_f32_e32 v16, v16
	v_rcp_f32_e32 v14, v14
	v_rcp_f32_e32 v11, v11
	v_rcp_f32_e32 v10, v10
	v_rcp_f32_e32 v0, v0
	v_mul_f32_e32 v5, v5, v12
	v_mul_f32_e32 v4, v4, v13
	v_mul_f32_e32 v3, v3, v15
	v_mul_f32_e32 v2, v2, v16
	v_mul_f32_e32 v7, v7, v14
	v_mul_f32_e32 v6, v6, v11
	v_mul_f32_e32 v8, v8, v10
	v_mul_f32_e32 v0, v9, v0
	v_cvt_pk_bf16_f32 v2, v2, v3
	v_cvt_pk_bf16_f32 v3, v4, v5
	v_cvt_pk_bf16_f32 v4, v6, v7
	v_cvt_pk_bf16_f32 v5, v8, v0
	global_store_dwordx4 v[26:27], v[2:5], off offset:2048
	s_barrier
